# GEMM1: both wave halves run the unit epilogue concurrently (leading half takes an extra barrier at K-loop exit, trailing half re-offsets with one before the next unit); the instruction-cache-cold epil
# speedup vs baseline: 1.0168x; 1.0154x over previous
.LBB0_238:
	s_and_b64 vcc, exec, s[2:3]
	s_cbranch_vccnz .LBB0_539
	s_cmpk_gt_u32 s85, 0xff
	s_cbranch_scc0 .Lus2
	s_barrier
.Lus2:
.LBB0_239:
	s_mov_b32 s2, s20
	s_add_i32 s20, s20, 1
	s_cmp_lt_u32 s2, 3
	s_cselect_b64 s[2:3], -1, 0
	s_and_b64 s[36:37], s[16:17], s[2:3]
	s_xor_b64 s[2:3], s[36:37], -1
	s_mov_b64 s[0:1], s[68:69]
	s_mov_b64 s[4:5], s[80:81]
	s_mov_b32 s24, s74
	s_mov_b32 s21, s6
	s_and_b64 vcc, exec, s[2:3]
	s_cbranch_vccnz .LBB0_241
	s_lshl_b32 s6, s20, 5
	s_add_i32 s6, s6, s18
	s_ashr_i32 s22, s6, 3
	s_cmp_eq_u32 s22, 15
	s_cselect_b64 s[6:7], -1, 0
	s_and_b64 s[6:7], s[6:7], s[14:15]
	s_and_b64 s[6:7], s[6:7], exec
	s_cselect_b32 s6, s19, s22
	s_cselect_b32 s74, 64, s19

.LBB0_242:
	s_add_u32 s4, s0, 0xfffc0080
	s_addc_u32 s5, s1, -1
	s_add_i32 vcc_lo, 0, 0x10000
	v_add_u32_e32 v128, vcc_lo, v162
	ds_read_b128 v[142:145], v128
	ds_read_b128 v[146:149], v128 offset:1024
	ds_read_b128 v[150:153], v128 offset:2048
	ds_read_b128 v[154:157], v128 offset:3072
	s_cmp_eq_u32 s75, 12
	s_cselect_b32 s37, s22, s5
	s_cselect_b32 s36, s23, s4
	s_cselect_b32 s5, s7, s39
	s_cselect_b32 s4, s25, s38
	v_lshl_add_u64 v[196:197], s[0:1], 0, v[138:139]
	s_add_i32 m0, s95, 0xc000
	ds_read_b128 v[164:167], v163
	ds_read_b128 v[168:171], v163 offset:1024
	ds_read_b128 v[172:175], v163 offset:2048
	ds_read_b128 v[176:179], v163 offset:3072
	ds_read_b128 v[180:183], v163 offset:4096
	ds_read_b128 v[184:187], v163 offset:5120
	ds_read_b128 v[188:191], v163 offset:6144
	ds_read_b128 v[192:195], v163 offset:7168
	global_load_lds_dwordx4 v[196:197], off
	v_lshl_add_u64 v[196:197], s[0:1], 0, v[140:141]
	s_add_i32 m0, s95, 0xe000
	s_nop 0
	global_load_lds_dwordx4 v[196:197], off
	s_waitcnt lgkmcnt(8)
	s_barrier
	s_waitcnt lgkmcnt(0)
	s_setprio 1
	s_waitcnt lgkmcnt(0)
	v_mfma_f32_16x16x32_bf16 v[124:127], v[142:145], v[164:167], v[124:127]
	v_mfma_f32_16x16x32_bf16 v[120:123], v[150:153], v[164:167], v[120:123]
	v_mfma_f32_16x16x32_bf16 v[108:111], v[142:145], v[172:175], v[108:111]
	v_mfma_f32_16x16x32_bf16 v[104:107], v[150:153], v[172:175], v[104:107]
	v_mfma_f32_16x16x32_bf16 v[92:95], v[142:145], v[180:183], v[92:95]
	v_mfma_f32_16x16x32_bf16 v[88:91], v[150:153], v[180:183], v[88:91]
	v_mfma_f32_16x16x32_bf16 v[76:79], v[142:145], v[188:191], v[76:79]
	v_mfma_f32_16x16x32_bf16 v[72:75], v[150:153], v[188:191], v[72:75]
	v_mfma_f32_16x16x32_bf16 v[124:127], v[146:149], v[168:171], v[124:127]
	v_mfma_f32_16x16x32_bf16 v[120:123], v[154:157], v[168:171], v[120:123]
	v_mfma_f32_16x16x32_bf16 v[108:111], v[146:149], v[176:179], v[108:111]
	v_mfma_f32_16x16x32_bf16 v[104:107], v[154:157], v[176:179], v[104:107]
	v_mfma_f32_16x16x32_bf16 v[92:95], v[146:149], v[184:187], v[92:95]
	v_mfma_f32_16x16x32_bf16 v[88:91], v[154:157], v[184:187], v[88:91]
	v_mfma_f32_16x16x32_bf16 v[76:79], v[146:149], v[192:195], v[76:79]
	v_mfma_f32_16x16x32_bf16 v[72:75], v[154:157], v[192:195], v[72:75]
	s_setprio 0
	s_barrier
	s_add_i32 s26, 0, 0x14000
	s_add_i32 s27, vcc_lo, s87
	v_add_u32_e32 v128, s26, v162
	v_lshl_add_u64 v[200:201], s[4:5], 0, v[132:133]
	s_mov_b32 m0, s27
	ds_read_b128 v[196:199], v128
	ds_read_b128 v[210:213], v128 offset:1024
	ds_read_b128 v[214:217], v128 offset:2048
	ds_read_b128 v[218:221], v128 offset:3072
	global_load_lds_dwordx4 v[200:201], off
	v_lshl_add_u64 v[222:223], s[4:5], 0, v[136:137]
	s_add_i32 m0, s27, 0x2000
	s_nop 0
	global_load_lds_dwordx4 v[222:223], off
	s_barrier
	s_waitcnt lgkmcnt(0)
	s_setprio 1
	s_waitcnt lgkmcnt(0)
	v_mfma_f32_16x16x32_bf16 v[116:119], v[196:199], v[164:167], v[116:119]
	v_mfma_f32_16x16x32_bf16 v[112:115], v[214:217], v[164:167], v[112:115]
	v_mfma_f32_16x16x32_bf16 v[100:103], v[196:199], v[172:175], v[100:103]
	v_mfma_f32_16x16x32_bf16 v[96:99], v[214:217], v[172:175], v[96:99]
	v_mfma_f32_16x16x32_bf16 v[84:87], v[196:199], v[180:183], v[84:87]
	v_mfma_f32_16x16x32_bf16 v[80:83], v[214:217], v[180:183], v[80:83]
	v_mfma_f32_16x16x32_bf16 v[68:71], v[196:199], v[188:191], v[68:71]
	v_mfma_f32_16x16x32_bf16 v[64:67], v[214:217], v[188:191], v[64:67]
	v_mfma_f32_16x16x32_bf16 v[116:119], v[210:213], v[168:171], v[116:119]
	v_mfma_f32_16x16x32_bf16 v[112:115], v[218:221], v[168:171], v[112:115]
	v_mfma_f32_16x16x32_bf16 v[100:103], v[210:213], v[176:179], v[100:103]
	v_mfma_f32_16x16x32_bf16 v[96:99], v[218:221], v[176:179], v[96:99]
	v_mfma_f32_16x16x32_bf16 v[84:87], v[210:213], v[184:187], v[84:87]
	v_mfma_f32_16x16x32_bf16 v[80:83], v[218:221], v[184:187], v[80:83]
	v_mfma_f32_16x16x32_bf16 v[68:71], v[210:213], v[192:195], v[68:71]
	v_mfma_f32_16x16x32_bf16 v[64:67], v[218:221], v[192:195], v[64:67]
	s_setprio 0
	s_mov_b32 m0, s95
	v_lshl_add_u64 v[224:225], s[36:37], 0, v[130:131]
	s_barrier
	ds_read_b128 v[164:167], v163 offset:16384
	ds_read_b128 v[168:171], v163 offset:17408
	ds_read_b128 v[172:175], v163 offset:18432
	ds_read_b128 v[176:179], v163 offset:19456
	ds_read_b128 v[180:183], v163 offset:20480
	ds_read_b128 v[184:187], v163 offset:21504
	ds_read_b128 v[188:191], v163 offset:22528
	ds_read_b128 v[192:195], v163 offset:23552
	global_load_lds_dwordx4 v[224:225], off
	v_lshl_add_u64 v[226:227], s[36:37], 0, v[134:135]
	s_mov_b32 m0, s97
	s_nop 0
	global_load_lds_dwordx4 v[226:227], off
	s_barrier
	s_waitcnt lgkmcnt(0)
	s_setprio 1
	s_waitcnt lgkmcnt(0)
	v_mfma_f32_16x16x32_bf16 v[60:63], v[142:145], v[164:167], v[60:63]
	v_mfma_f32_16x16x32_bf16 v[56:59], v[150:153], v[164:167], v[56:59]
	v_mfma_f32_16x16x32_bf16 v[44:47], v[142:145], v[172:175], v[44:47]
	v_mfma_f32_16x16x32_bf16 v[40:43], v[150:153], v[172:175], v[40:43]
	v_mfma_f32_16x16x32_bf16 v[28:31], v[142:145], v[180:183], v[28:31]
	v_mfma_f32_16x16x32_bf16 v[24:27], v[150:153], v[180:183], v[24:27]
	v_mfma_f32_16x16x32_bf16 v[12:15], v[142:145], v[188:191], v[12:15]
	v_mfma_f32_16x16x32_bf16 v[8:11], v[150:153], v[188:191], v[8:11]
	v_mfma_f32_16x16x32_bf16 v[60:63], v[146:149], v[168:171], v[60:63]
	v_mfma_f32_16x16x32_bf16 v[56:59], v[154:157], v[168:171], v[56:59]
	v_mfma_f32_16x16x32_bf16 v[44:47], v[146:149], v[176:179], v[44:47]
	v_mfma_f32_16x16x32_bf16 v[40:43], v[154:157], v[176:179], v[40:43]
	v_mfma_f32_16x16x32_bf16 v[28:31], v[146:149], v[184:187], v[28:31]
	v_mfma_f32_16x16x32_bf16 v[24:27], v[154:157], v[184:187], v[24:27]
	v_mfma_f32_16x16x32_bf16 v[12:15], v[146:149], v[192:195], v[12:15]
	v_mfma_f32_16x16x32_bf16 v[8:11], v[154:157], v[192:195], v[8:11]
	s_setprio 0
	s_barrier
	s_add_u32 vcc_lo, s4, 0x40000
	s_addc_u32 vcc_hi, s5, 0
	s_add_i32 s26, s26, s87
	v_lshl_add_u64 v[142:143], vcc, 0, v[132:133]
	s_mov_b32 m0, s26
	s_nop 0
	global_load_lds_dwordx4 v[142:143], off
	v_lshl_add_u64 v[142:143], vcc, 0, v[136:137]
	s_add_i32 m0, s26, 0x2000
	s_nop 0
	global_load_lds_dwordx4 v[142:143], off
	s_waitcnt vmcnt(6)
	s_barrier
	s_setprio 1
	v_mfma_f32_16x16x32_bf16 v[52:55], v[196:199], v[164:167], v[52:55]
	v_mfma_f32_16x16x32_bf16 v[48:51], v[214:217], v[164:167], v[48:51]
	v_mfma_f32_16x16x32_bf16 v[36:39], v[196:199], v[172:175], v[36:39]
	v_mfma_f32_16x16x32_bf16 v[32:35], v[214:217], v[172:175], v[32:35]
	v_mfma_f32_16x16x32_bf16 v[20:23], v[196:199], v[180:183], v[20:23]
	v_mfma_f32_16x16x32_bf16 v[16:19], v[214:217], v[180:183], v[16:19]
	v_mfma_f32_16x16x32_bf16 v[4:7], v[196:199], v[188:191], v[4:7]
	v_mfma_f32_16x16x32_bf16 v[0:3], v[214:217], v[188:191], v[0:3]
	v_mfma_f32_16x16x32_bf16 v[52:55], v[210:213], v[168:171], v[52:55]
	v_mfma_f32_16x16x32_bf16 v[48:51], v[218:221], v[168:171], v[48:51]
	v_mfma_f32_16x16x32_bf16 v[36:39], v[210:213], v[176:179], v[36:39]
	v_mfma_f32_16x16x32_bf16 v[32:35], v[218:221], v[176:179], v[32:35]
	v_mfma_f32_16x16x32_bf16 v[20:23], v[210:213], v[184:187], v[20:23]
	v_mfma_f32_16x16x32_bf16 v[16:19], v[218:221], v[184:187], v[16:19]
	v_mfma_f32_16x16x32_bf16 v[4:7], v[210:213], v[192:195], v[4:7]
	v_mfma_f32_16x16x32_bf16 v[0:3], v[218:221], v[192:195], v[0:3]
	s_setprio 0
	s_add_i32 s26, 0, 0x18000
	v_add_u32_e32 v128, s26, v162
	s_barrier
	ds_read_b128 v[142:145], v128
	ds_read_b128 v[146:149], v128 offset:1024
	ds_read_b128 v[150:153], v128 offset:2048
	ds_read_b128 v[154:157], v128 offset:3072
	s_add_u32 s36, s36, 0x40000
	s_addc_u32 s37, s37, 0
	s_mov_b32 m0, s33
	v_lshl_add_u64 v[196:197], s[36:37], 0, v[130:131]
	ds_read_b128 v[164:167], v163 offset:32768
	ds_read_b128 v[168:171], v163 offset:33792
	ds_read_b128 v[172:175], v163 offset:34816
	ds_read_b128 v[176:179], v163 offset:35840
	ds_read_b128 v[180:183], v163 offset:36864
	ds_read_b128 v[184:187], v163 offset:37888
	ds_read_b128 v[188:191], v163 offset:38912
	ds_read_b128 v[192:195], v163 offset:39936
	global_load_lds_dwordx4 v[196:197], off
	v_lshl_add_u64 v[196:197], s[36:37], 0, v[134:135]
	s_mov_b32 m0, s93
	s_nop 0
	global_load_lds_dwordx4 v[196:197], off
	s_waitcnt lgkmcnt(8)
	s_barrier
	s_waitcnt lgkmcnt(0)
	s_setprio 1
	s_waitcnt lgkmcnt(0)
	v_mfma_f32_16x16x32_bf16 v[124:127], v[142:145], v[164:167], v[124:127]
	v_mfma_f32_16x16x32_bf16 v[120:123], v[150:153], v[164:167], v[120:123]
	v_mfma_f32_16x16x32_bf16 v[108:111], v[142:145], v[172:175], v[108:111]
	v_mfma_f32_16x16x32_bf16 v[104:107], v[150:153], v[172:175], v[104:107]
	v_mfma_f32_16x16x32_bf16 v[92:95], v[142:145], v[180:183], v[92:95]
	v_mfma_f32_16x16x32_bf16 v[88:91], v[150:153], v[180:183], v[88:91]
	v_mfma_f32_16x16x32_bf16 v[76:79], v[142:145], v[188:191], v[76:79]
	v_mfma_f32_16x16x32_bf16 v[72:75], v[150:153], v[188:191], v[72:75]
	v_mfma_f32_16x16x32_bf16 v[124:127], v[146:149], v[168:171], v[124:127]
	v_mfma_f32_16x16x32_bf16 v[120:123], v[154:157], v[168:171], v[120:123]
	v_mfma_f32_16x16x32_bf16 v[108:111], v[146:149], v[176:179], v[108:111]
	v_mfma_f32_16x16x32_bf16 v[104:107], v[154:157], v[176:179], v[104:107]
	v_mfma_f32_16x16x32_bf16 v[92:95], v[146:149], v[184:187], v[92:95]
	v_mfma_f32_16x16x32_bf16 v[88:91], v[154:157], v[184:187], v[88:91]
	v_mfma_f32_16x16x32_bf16 v[76:79], v[146:149], v[192:195], v[76:79]
	v_mfma_f32_16x16x32_bf16 v[72:75], v[154:157], v[192:195], v[72:75]
	s_setprio 0
	s_barrier
	s_add_i32 s27, 0, 0x1c000
	s_add_i32 s26, s26, s87
	v_add_u32_e32 v128, s27, v162
	v_lshl_add_u64 v[200:201], v[200:201], 0, s[82:83]
	s_mov_b32 m0, s26
	ds_read_b128 v[196:199], v128
	ds_read_b128 v[210:213], v128 offset:1024
	ds_read_b128 v[214:217], v128 offset:2048
	ds_read_b128 v[218:221], v128 offset:3072
	global_load_lds_dwordx4 v[200:201], off
	v_lshl_add_u64 v[200:201], v[222:223], 0, s[82:83]
	s_add_i32 m0, s26, 0x2000
	s_nop 0
	global_load_lds_dwordx4 v[200:201], off
	s_barrier
	s_waitcnt lgkmcnt(0)
	s_setprio 1
	s_waitcnt lgkmcnt(0)
	v_mfma_f32_16x16x32_bf16 v[116:119], v[196:199], v[164:167], v[116:119]
	v_mfma_f32_16x16x32_bf16 v[112:115], v[214:217], v[164:167], v[112:115]
	v_mfma_f32_16x16x32_bf16 v[100:103], v[196:199], v[172:175], v[100:103]
	v_mfma_f32_16x16x32_bf16 v[96:99], v[214:217], v[172:175], v[96:99]
	v_mfma_f32_16x16x32_bf16 v[84:87], v[196:199], v[180:183], v[84:87]
	v_mfma_f32_16x16x32_bf16 v[80:83], v[214:217], v[180:183], v[80:83]
	v_mfma_f32_16x16x32_bf16 v[68:71], v[196:199], v[188:191], v[68:71]
	v_mfma_f32_16x16x32_bf16 v[64:67], v[214:217], v[188:191], v[64:67]
	v_mfma_f32_16x16x32_bf16 v[116:119], v[210:213], v[168:171], v[116:119]
	v_mfma_f32_16x16x32_bf16 v[112:115], v[218:221], v[168:171], v[112:115]
	v_mfma_f32_16x16x32_bf16 v[100:103], v[210:213], v[176:179], v[100:103]
	v_mfma_f32_16x16x32_bf16 v[96:99], v[218:221], v[176:179], v[96:99]
	v_mfma_f32_16x16x32_bf16 v[84:87], v[210:213], v[184:187], v[84:87]
	v_mfma_f32_16x16x32_bf16 v[80:83], v[218:221], v[184:187], v[80:83]
	v_mfma_f32_16x16x32_bf16 v[68:71], v[210:213], v[192:195], v[68:71]
	v_mfma_f32_16x16x32_bf16 v[64:67], v[218:221], v[192:195], v[64:67]
	s_setprio 0
	s_mov_b32 m0, s12
	v_lshl_add_u64 v[200:201], v[224:225], 0, s[82:83]
	s_barrier
	ds_read_b128 v[164:167], v163 offset:49152
	ds_read_b128 v[168:171], v163 offset:50176
	ds_read_b128 v[172:175], v163 offset:51200
	ds_read_b128 v[176:179], v163 offset:52224
	ds_read_b128 v[180:183], v163 offset:53248
	ds_read_b128 v[184:187], v163 offset:54272
	ds_read_b128 v[188:191], v163 offset:55296
	ds_read_b128 v[192:195], v163 offset:56320
	global_load_lds_dwordx4 v[200:201], off
	v_lshl_add_u64 v[200:201], v[226:227], 0, s[82:83]
	s_mov_b32 m0, s13
	s_nop 0
	global_load_lds_dwordx4 v[200:201], off
	s_barrier
	s_waitcnt lgkmcnt(0)
	s_setprio 1
	s_waitcnt lgkmcnt(0)
	v_mfma_f32_16x16x32_bf16 v[60:63], v[142:145], v[164:167], v[60:63]
	v_mfma_f32_16x16x32_bf16 v[56:59], v[150:153], v[164:167], v[56:59]
	v_mfma_f32_16x16x32_bf16 v[44:47], v[142:145], v[172:175], v[44:47]
	v_mfma_f32_16x16x32_bf16 v[40:43], v[150:153], v[172:175], v[40:43]
	v_mfma_f32_16x16x32_bf16 v[28:31], v[142:145], v[180:183], v[28:31]
	v_mfma_f32_16x16x32_bf16 v[24:27], v[150:153], v[180:183], v[24:27]
	v_mfma_f32_16x16x32_bf16 v[12:15], v[142:145], v[188:191], v[12:15]
	v_mfma_f32_16x16x32_bf16 v[8:11], v[150:153], v[188:191], v[8:11]
	v_mfma_f32_16x16x32_bf16 v[60:63], v[146:149], v[168:171], v[60:63]
	v_mfma_f32_16x16x32_bf16 v[56:59], v[154:157], v[168:171], v[56:59]
	v_mfma_f32_16x16x32_bf16 v[44:47], v[146:149], v[176:179], v[44:47]
	v_mfma_f32_16x16x32_bf16 v[40:43], v[154:157], v[176:179], v[40:43]
	v_mfma_f32_16x16x32_bf16 v[28:31], v[146:149], v[184:187], v[28:31]
	v_mfma_f32_16x16x32_bf16 v[24:27], v[154:157], v[184:187], v[24:27]
	v_mfma_f32_16x16x32_bf16 v[12:15], v[146:149], v[192:195], v[12:15]
	v_mfma_f32_16x16x32_bf16 v[8:11], v[154:157], v[192:195], v[8:11]
	s_setprio 0
	s_barrier
	s_add_u32 s4, s4, 0x40080
	s_addc_u32 s5, s5, 0
	s_add_i32 s26, s27, s87
	v_lshl_add_u64 v[142:143], s[4:5], 0, v[132:133]
	s_mov_b32 m0, s26
	s_nop 0
	global_load_lds_dwordx4 v[142:143], off
	v_lshl_add_u64 v[142:143], s[4:5], 0, v[136:137]
	s_add_i32 m0, s26, 0x2000
	s_nop 0
	global_load_lds_dwordx4 v[142:143], off
	s_waitcnt vmcnt(6)
	s_barrier
	s_setprio 1
	v_mfma_f32_16x16x32_bf16 v[52:55], v[196:199], v[164:167], v[52:55]
	v_mfma_f32_16x16x32_bf16 v[48:51], v[214:217], v[164:167], v[48:51]
	v_mfma_f32_16x16x32_bf16 v[36:39], v[196:199], v[172:175], v[36:39]
	v_mfma_f32_16x16x32_bf16 v[32:35], v[214:217], v[172:175], v[32:35]
	v_mfma_f32_16x16x32_bf16 v[20:23], v[196:199], v[180:183], v[20:23]
	v_mfma_f32_16x16x32_bf16 v[16:19], v[214:217], v[180:183], v[16:19]
	v_mfma_f32_16x16x32_bf16 v[4:7], v[196:199], v[188:191], v[4:7]
	v_mfma_f32_16x16x32_bf16 v[0:3], v[214:217], v[188:191], v[0:3]
	v_mfma_f32_16x16x32_bf16 v[52:55], v[210:213], v[168:171], v[52:55]
	v_mfma_f32_16x16x32_bf16 v[48:51], v[218:221], v[168:171], v[48:51]
	v_mfma_f32_16x16x32_bf16 v[36:39], v[210:213], v[176:179], v[36:39]
	v_mfma_f32_16x16x32_bf16 v[32:35], v[218:221], v[176:179], v[32:35]
	v_mfma_f32_16x16x32_bf16 v[20:23], v[210:213], v[184:187], v[20:23]
	v_mfma_f32_16x16x32_bf16 v[16:19], v[218:221], v[184:187], v[16:19]
	v_mfma_f32_16x16x32_bf16 v[4:7], v[210:213], v[192:195], v[4:7]
	v_mfma_f32_16x16x32_bf16 v[0:3], v[218:221], v[192:195], v[0:3]
	s_setprio 0
	s_add_i32 s75, s75, 2
	s_add_u32 s0, s0, 0x100
	s_addc_u32 s1, s1, 0
	s_add_u32 s38, s38, 0x100
	s_addc_u32 s39, s39, 0
	s_cmp_gt_u32 s75, 13
	s_barrier
	s_cbranch_scc0 .LBB0_242
	s_cmpk_gt_u32 s85, 0xff
	s_cbranch_scc1 .Lus1
	s_barrier
.Lus1:
	s_cmp_lt_u32 s21, 10
	s_cselect_b32 s1, 2, 3
	s_cmp_gt_u32 s21, 7
	s_cselect_b32 s1, s1, 4
	s_cmp_gt_u32 s21, 3
	s_cselect_b32 s1, s1, 1
	s_cmp_gt_i32 s21, 1
	s_cselect_b32 s7, s1, 0
	s_and_b32 s1, s21, -2
	s_and_b32 s22, s21, -4
	s_add_i32 s23, s21, 4
	s_lshl_b32 s21, s21, 1
	s_add_i32 s25, s21, -4
	s_cmp_eq_u32 s1, 8
	s_cselect_b64 s[36:37], -1, 0
	v_mov_b32_e32 v128, v202
	s_and_b64 s[4:5], s[36:37], exec
	s_cselect_b32 s1, s25, s21
	v_readfirstlane_b32 s0, v128
	s_cmp_eq_u32 s22, 4
	s_cselect_b32 s21, s23, s1
	s_lshr_b32 s1, s0, 1
	s_ashr_i32 s0, s0, 2
	s_andn2_b32 s0, s0, 63
	s_ashr_i32 s75, s21, 31
	s_and_b32 s22, s1, 0x60
	v_and_or_b32 v164, v128, 15, s0
	s_lshl_b32 s23, s24, 1
	s_mul_i32 s0, s24, 0x48
	s_mul_hi_i32 s1, s23, 36
	s_add_u32 s0, s0, s21
	s_addc_u32 s1, s1, s75
	s_lshl_b64 s[0:1], s[0:1], 15
	s_add_u32 s0, s70, s0
	s_addc_u32 s1, s71, s1
	s_lshl_b32 s22, s22, 1
	v_bfe_u32 v165, v128, 4, 2
	s_add_u32 s0, s0, s22
	s_addc_u32 s1, s1, 0
	v_lshlrev_b32_e32 v128, 4, v165
	v_lshlrev_b32_e32 v142, 7, v164
	v_lshl_add_u64 v[144:145], s[0:1], 0, v[128:129]
	v_ashrrev_i32_e32 v143, 31, v142
	v_cmp_eq_u32_e64 s[4:5], 0, v165
	v_lshl_add_u64 v[146:147], v[142:143], 1, v[144:145]
	s_cmp_lt_i32 s7, 3
	s_mov_b64 s[0:1], -1
	s_cbranch_scc1 .LBB0_249
	s_cmp_gt_i32 s7, 3
	s_cbranch_scc0 .LBB0_246
	v_and_b32_e32 v149, 0x7fffffff, v125
	v_and_b32_e32 v148, 0x7fffffff, v124
	v_pk_fma_f32 v[148:149], v[148:149], s[84:85], 1.0 op_sel_hi:[1,0,0]
	v_mov_b64_e32 v[150:151], s[88:89]
	v_rcp_f32_e32 v148, v148
	v_rcp_f32_e32 v149, v149
	v_pk_mul_f32 v[154:155], v[124:125], v[124:125]
	v_and_b32_e32 v157, 0x7fffffff, v127
	v_pk_mul_f32 v[154:155], v[154:155], s[96:97] op_sel_hi:[1,0]
	v_pk_fma_f32 v[152:153], v[148:149], s[86:87], v[150:151] op_sel_hi:[1,0,0]
	v_exp_f32_e32 v154, v154
	v_pk_fma_f32 v[152:153], v[148:149], v[152:153], s[90:91] op_sel_hi:[1,1,0]
	v_exp_f32_e32 v155, v155
	v_pk_fma_f32 v[152:153], v[148:149], v[152:153], s[92:93] op_sel_hi:[1,1,0]
	v_and_b32_e32 v156, 0x7fffffff, v126
	v_pk_fma_f32 v[152:153], v[148:149], v[152:153], s[94:95] op_sel_hi:[1,1,0]
	v_pk_fma_f32 v[156:157], v[156:157], s[84:85], 1.0 op_sel_hi:[1,0,0]
	v_pk_mul_f32 v[148:149], v[148:149], v[152:153]
	v_rcp_f32_e32 v156, v156
	v_rcp_f32_e32 v157, v157
	v_pk_mul_f32 v[148:149], v[154:155], v[148:149]
	v_cmp_gt_f32_e32 vcc, 0, v124
	v_pk_mul_f32 v[154:155], v[124:125], v[148:149]
	v_pk_fma_f32 v[148:149], v[124:125], v[148:149], v[124:125] neg_lo:[1,0,0] neg_hi:[1,0,0]
	v_pk_mul_f32 v[152:153], v[126:127], v[126:127]
	v_cndmask_b32_e32 v148, v148, v154, vcc
	v_cmp_gt_f32_e32 vcc, 0, v125
	v_pk_mul_f32 v[152:153], v[152:153], s[96:97] op_sel_hi:[1,0]
	v_and_b32_e32 v169, 0x7fffffff, v123
	v_cndmask_b32_e32 v149, v149, v155, vcc
	v_pk_fma_f32 v[154:155], v[156:157], s[86:87], v[150:151] op_sel_hi:[1,0,0]
	v_exp_f32_e32 v152, v152
	v_pk_fma_f32 v[154:155], v[156:157], v[154:155], s[90:91] op_sel_hi:[1,1,0]
	v_exp_f32_e32 v153, v153
	v_pk_fma_f32 v[154:155], v[156:157], v[154:155], s[92:93] op_sel_hi:[1,1,0]
	v_cmp_gt_f32_e32 vcc, 0, v126
	v_pk_fma_f32 v[154:155], v[156:157], v[154:155], s[94:95] op_sel_hi:[1,1,0]
	v_and_b32_e32 v168, 0x7fffffff, v122
	v_pk_mul_f32 v[154:155], v[156:157], v[154:155]
	v_and_b32_e32 v157, 0x7fffffff, v121
	v_and_b32_e32 v156, 0x7fffffff, v120
	v_pk_fma_f32 v[156:157], v[156:157], s[84:85], 1.0 op_sel_hi:[1,0,0]
	v_pk_mul_f32 v[152:153], v[152:153], v[154:155]
	v_rcp_f32_e32 v156, v156
	v_rcp_f32_e32 v157, v157
	v_pk_mul_f32 v[154:155], v[126:127], v[152:153]
	v_pk_fma_f32 v[152:153], v[126:127], v[152:153], v[126:127] neg_lo:[1,0,0] neg_hi:[1,0,0]
	v_pk_fma_f32 v[168:169], v[168:169], s[84:85], 1.0 op_sel_hi:[1,0,0]
	v_cndmask_b32_e32 v152, v152, v154, vcc
	v_cmp_gt_f32_e32 vcc, 0, v127
	v_rcp_f32_e32 v168, v168
	v_rcp_f32_e32 v169, v169
	v_cndmask_b32_e32 v153, v153, v155, vcc
	v_pk_fma_f32 v[154:155], v[156:157], s[86:87], v[150:151] op_sel_hi:[1,0,0]
	v_pk_mul_f32 v[166:167], v[120:121], v[120:121]
	v_pk_fma_f32 v[154:155], v[156:157], v[154:155], s[90:91] op_sel_hi:[1,1,0]
	v_pk_mul_f32 v[166:167], v[166:167], s[96:97] op_sel_hi:[1,0]
	v_pk_fma_f32 v[154:155], v[156:157], v[154:155], s[92:93] op_sel_hi:[1,1,0]
	v_exp_f32_e32 v166, v166
	v_pk_fma_f32 v[154:155], v[156:157], v[154:155], s[94:95] op_sel_hi:[1,1,0]
	v_exp_f32_e32 v167, v167
	v_pk_mul_f32 v[154:155], v[156:157], v[154:155]
	v_pk_mul_f32 v[156:157], v[122:123], v[122:123]
	v_pk_fma_f32 v[150:151], v[168:169], s[86:87], v[150:151] op_sel_hi:[1,0,0]
	v_pk_mul_f32 v[156:157], v[156:157], s[96:97] op_sel_hi:[1,0]
	v_pk_fma_f32 v[150:151], v[168:169], v[150:151], s[90:91] op_sel_hi:[1,1,0]
	v_exp_f32_e32 v156, v156
	v_exp_f32_e32 v157, v157
	v_pk_fma_f32 v[150:151], v[168:169], v[150:151], s[92:93] op_sel_hi:[1,1,0]
	v_pk_mul_f32 v[154:155], v[166:167], v[154:155]
	v_pk_fma_f32 v[150:151], v[168:169], v[150:151], s[94:95] op_sel_hi:[1,1,0]
	v_pk_mul_f32 v[166:167], v[120:121], v[154:155]
	v_pk_fma_f32 v[154:155], v[120:121], v[154:155], v[120:121] neg_lo:[1,0,0] neg_hi:[1,0,0]
	v_cmp_gt_f32_e32 vcc, 0, v120
	v_pk_mul_f32 v[150:151], v[168:169], v[150:151]
	v_mul_f32_e32 v128, 0xbfb8aa3b, v116
	v_cndmask_b32_e32 v154, v154, v166, vcc
	v_cmp_gt_f32_e32 vcc, 0, v121
	v_pk_mul_f32 v[150:151], v[156:157], v[150:151]
	v_exp_f32_e32 v128, v128
	v_cndmask_b32_e32 v155, v155, v167, vcc
	v_pk_mul_f32 v[156:157], v[122:123], v[150:151]
	v_pk_fma_f32 v[150:151], v[122:123], v[150:151], v[122:123] neg_lo:[1,0,0] neg_hi:[1,0,0]
	v_cmp_gt_f32_e32 vcc, 0, v122
	v_add_f32_e32 v128, 1.0, v128
	s_mov_b64 s[0:1], 0
	v_cndmask_b32_e32 v150, v150, v156, vcc
	v_mul_f32_e32 v156, 0xbfb8aa3b, v117
	v_exp_f32_e32 v166, v156
	v_cmp_gt_f32_e32 vcc, 0, v123
	v_rcp_f32_e32 v156, v128
	v_add_f32_e32 v128, 1.0, v166
	v_cndmask_b32_e32 v151, v151, v157, vcc
	v_mul_f32_e32 v157, 0xbfb8aa3b, v118
	v_exp_f32_e32 v166, v157
	v_mul_f32_e32 v157, 0xbfb8aa3b, v119
	v_exp_f32_e32 v167, v157
	v_rcp_f32_e32 v157, v128
	v_add_f32_e32 v128, 1.0, v166
	v_rcp_f32_e32 v166, v128
	v_add_f32_e32 v128, 1.0, v167
	v_mul_f32_e32 v167, 0xbfb8aa3b, v112
	v_exp_f32_e32 v168, v167
	v_mul_f32_e32 v167, 0xbfb8aa3b, v113
	v_exp_f32_e32 v169, v167
	v_rcp_f32_e32 v167, v128
	v_add_f32_e32 v128, 1.0, v168
	v_rcp_f32_e32 v168, v128
	v_add_f32_e32 v128, 1.0, v169
	v_mul_f32_e32 v169, 0xbfb8aa3b, v114
	v_exp_f32_e32 v170, v169
	v_mul_f32_e32 v169, 0xbfb8aa3b, v115
	v_exp_f32_e32 v171, v169
	v_rcp_f32_e32 v169, v128
	v_add_f32_e32 v128, 1.0, v170
	v_rcp_f32_e32 v170, v128
	v_add_f32_e32 v128, 1.0, v171
	v_rcp_f32_e32 v171, v128
	v_pk_mul_f32 v[156:157], v[116:117], v[156:157]
	v_pk_mul_f32 v[168:169], v[112:113], v[168:169]
	v_pk_mul_f32 v[166:167], v[118:119], v[166:167]
	v_pk_mul_f32 v[170:171], v[114:115], v[170:171]
	v_pk_mul_f32 v[148:149], v[148:149], v[156:157]
	v_pk_mul_f32 v[156:157], v[150:151], v[170:171]
	v_pk_mul_f32 v[150:151], v[154:155], v[168:169]
	v_pk_mul_f32 v[152:153], v[152:153], v[166:167]
	v_cvt_pk_bf16_f32 v148, v148, v149
	v_cvt_pk_bf16_f32 v150, v150, v151
	v_cvt_pk_bf16_f32 v151, v156, v157
	s_nop 0
	v_cvt_pk_bf16_f32 v149, v152, v153
	global_store_dwordx4 v[146:147], v[148:151], off

.LBB0_539:
	s_waitcnt vmcnt(0)
	v_readlane_b32 s20, v234, 49
	s_cmpk_gt_u32 s85, 0xff
	v_readlane_b32 s21, v234, 50
	s_cbranch_scc1 .LBB0_541
.LBB0_541:
	v_readlane_b32 s80, v234, 43
	v_readlane_b32 s22, v234, 45
	v_readlane_b32 s24, v234, 47
	v_readlane_b32 s81, v234, 44
	v_readlane_b32 s23, v234, 46
	v_readlane_b32 s25, v234, 48
	s_barrier
	s_and_b64 vcc, exec, s[8:9]
	s_mov_b64 s[0:1], -1
	s_cbranch_vccnz .LBB0_218
